# ev_out GEMM phase fully hand-written: 128x64 tile LDS-DMA K-loop plus batched residual epilogue (replaces serialized prologue/epilogue chains)
# speedup vs baseline: 1.1212x; 1.0247x over previous
.LBB0_886:
	s_or_b64 exec, exec, s[0:1]
	s_and_b64 vcc, exec, s[40:41]
	s_waitcnt lgkmcnt(0)
	s_barrier
	s_cbranch_vccnz .LBB0_921
	s_mov_b32 s9, s33
.Leo_item:
	s_mul_hi_i32 s12, s9, 0x2aaaaaab
	s_lshr_b32 s13, s12, 31
	s_ashr_i32 s12, s12, 4
	s_add_i32 s12, s12, s13
	s_mul_i32 s13, s12, 0x60
	s_sub_i32 s13, s9, s13
	s_lshl_b32 s10, s13, 7
	s_lshl_b32 s11, s12, 6
	v_lshl_or_b32 v32, v183, 3, v191
	v_and_b32_e32 v33, 63, v32
	v_lshrrev_b32_e32 v34, 3, v33
	v_lshrrev_b32_e32 v35, 4, v33
	v_xor_b32_e32 v35, v35, v33
	v_and_b32_e32 v35, 7, v35
	v_lshlrev_b32_e32 v35, 4, v35
	s_movk_i32 s12, 0x800
	v_mad_u32_u24 v68, v34, s12, v35
	v_xor_b32_e32 v36, 64, v68
	v_add_u32_e32 v69, 0x3c00, v36
	v_add_u32_e32 v70, 0x7800, v68
	v_add_u32_e32 v71, 0xb400, v36
	v_and_b32_e32 v37, 31, v32
	v_bfe_u32 v38, v32, 5, 1
	v_bfe_u32 v39, v32, 1, 3
	v_xor_b32_e32 v39, v39, v38
	v_lshlrev_b32_e32 v39, 4, v39
	v_bfe_u32 v40, v32, 7, 1
	v_lshl_or_b32 v40, v40, 6, v37
	v_lshl_add_u32 v72, v40, 7, v39
	v_bfe_u32 v41, v32, 6, 1
	v_lshl_or_b32 v41, v41, 5, v37
	v_lshl_add_u32 v76, v41, 7, v39
	v_add_u32_e32 v76, 0x4000, v76
	v_xor_b32_e32 v73, 32, v72
	v_xor_b32_e32 v77, 32, v76
	v_xor_b32_e32 v74, 64, v72
	v_xor_b32_e32 v78, 64, v76
	v_xor_b32_e32 v75, 96, v72
	v_xor_b32_e32 v79, 96, v76
	v_lshrrev_b32_e32 v42, 6, v32
	s_nop 0
	v_readfirstlane_b32 s13, v42
	s_nop 3
	s_lshl_b32 s6, s13, 12
	s_lshl_b32 s7, s13, 11
	s_add_u32 s7, s7, 0x4000
	s_lshl_b32 s12, s13, 5
	s_add_u32 s12, s12, s10
	s_mul_i32 s12, s12, 0x800
	s_add_u32 s12, s12, 0x3000000
	s_add_u32 s0, s88, s12
	s_addc_u32 s1, s89, 0
	s_lshl_b32 s12, s13, 4
	s_add_u32 s12, s12, s11
	s_mul_i32 s12, s12, 0x800
	s_add_u32 s12, s12, 0x940000
	s_add_u32 s2, s90, s12
	s_addc_u32 s3, s91, 0
	s_add_u32 m0, s6, 0x0
	s_nop 0
	global_load_lds_dwordx4 v68, s[0:1] offset:0
	global_load_lds_dwordx4 v69, s[0:1] offset:1024
	global_load_lds_dwordx4 v70, s[0:1] offset:2048
	global_load_lds_dwordx4 v71, s[0:1] offset:3072
	s_add_u32 m0, s7, 0x0
	s_nop 0
	global_load_lds_dwordx4 v68, s[2:3] offset:0
	global_load_lds_dwordx4 v69, s[2:3] offset:1024
	s_add_u32 s0, s0, 0x80
	s_addc_u32 s1, s1, 0
	s_add_u32 s2, s2, 0x80
	s_addc_u32 s3, s3, 0
	s_add_u32 m0, s6, 0x8000
	s_nop 0
	global_load_lds_dwordx4 v68, s[0:1] offset:0
	global_load_lds_dwordx4 v69, s[0:1] offset:1024
	global_load_lds_dwordx4 v70, s[0:1] offset:2048
	global_load_lds_dwordx4 v71, s[0:1] offset:3072
	s_add_u32 m0, s7, 0x8000
	s_nop 0
	global_load_lds_dwordx4 v68, s[2:3] offset:0
	global_load_lds_dwordx4 v69, s[2:3] offset:1024
	s_add_u32 s0, s0, 0x80
	s_addc_u32 s1, s1, 0
	s_add_u32 s2, s2, 0x80
	s_addc_u32 s3, s3, 0
	v_mov_b32_e32 v0, 0
	v_mov_b32_e32 v1, 0
	v_mov_b32_e32 v2, 0
	v_mov_b32_e32 v3, 0
	v_mov_b32_e32 v4, 0
	v_mov_b32_e32 v5, 0
	v_mov_b32_e32 v6, 0
	v_mov_b32_e32 v7, 0
	v_mov_b32_e32 v8, 0
	v_mov_b32_e32 v9, 0
	v_mov_b32_e32 v10, 0
	v_mov_b32_e32 v11, 0
	v_mov_b32_e32 v12, 0
	v_mov_b32_e32 v13, 0
	v_mov_b32_e32 v14, 0
	v_mov_b32_e32 v15, 0
	v_mov_b32_e32 v16, 0
	v_mov_b32_e32 v17, 0
	v_mov_b32_e32 v18, 0
	v_mov_b32_e32 v19, 0
	v_mov_b32_e32 v20, 0
	v_mov_b32_e32 v21, 0
	v_mov_b32_e32 v22, 0
	v_mov_b32_e32 v23, 0
	v_mov_b32_e32 v24, 0
	v_mov_b32_e32 v25, 0
	v_mov_b32_e32 v26, 0
	v_mov_b32_e32 v27, 0
	v_mov_b32_e32 v28, 0
	v_mov_b32_e32 v29, 0
	v_mov_b32_e32 v30, 0
	v_mov_b32_e32 v31, 0
	s_movk_i32 s8, 7
	s_waitcnt vmcnt(6)
.Lgeo_loop:
	s_waitcnt vmcnt(6)
	s_barrier
	ds_read_b128 v[32:35], v72 offset:0
	ds_read_b128 v[40:43], v76 offset:0
	ds_read_b128 v[36:39], v72 offset:4096
	ds_read_b128 v[44:47], v73 offset:0
	ds_read_b128 v[52:55], v77 offset:0
	ds_read_b128 v[48:51], v73 offset:4096
	s_waitcnt lgkmcnt(3)
	v_mfma_f32_32x32x16_bf16 v[0:15], v[32:35], v[40:43], v[0:15]
	ds_read_b128 v[56:59], v74 offset:0
	ds_read_b128 v[64:67], v78 offset:0
	v_mfma_f32_32x32x16_bf16 v[16:31], v[36:39], v[40:43], v[16:31]
	ds_read_b128 v[60:63], v74 offset:4096
	s_waitcnt lgkmcnt(3)
	v_mfma_f32_32x32x16_bf16 v[0:15], v[44:47], v[52:55], v[0:15]
	ds_read_b128 v[32:35], v75 offset:0
	ds_read_b128 v[40:43], v79 offset:0
	v_mfma_f32_32x32x16_bf16 v[16:31], v[48:51], v[52:55], v[16:31]
	ds_read_b128 v[36:39], v75 offset:4096
	s_waitcnt lgkmcnt(3)
	v_mfma_f32_32x32x16_bf16 v[0:15], v[56:59], v[64:67], v[0:15]
	v_mfma_f32_32x32x16_bf16 v[16:31], v[60:63], v[64:67], v[16:31]
	s_waitcnt lgkmcnt(0)
	v_mfma_f32_32x32x16_bf16 v[0:15], v[32:35], v[40:43], v[0:15]
	v_mfma_f32_32x32x16_bf16 v[16:31], v[36:39], v[40:43], v[16:31]
	s_barrier
	s_add_u32 m0, s6, 0x0
	s_nop 0
	global_load_lds_dwordx4 v68, s[0:1] offset:0
	global_load_lds_dwordx4 v69, s[0:1] offset:1024
	global_load_lds_dwordx4 v70, s[0:1] offset:2048
	global_load_lds_dwordx4 v71, s[0:1] offset:3072
	s_add_u32 m0, s7, 0x0
	s_nop 0
	global_load_lds_dwordx4 v68, s[2:3] offset:0
	global_load_lds_dwordx4 v69, s[2:3] offset:1024
	s_add_u32 s0, s0, 0x80
	s_addc_u32 s1, s1, 0
	s_add_u32 s2, s2, 0x80
	s_addc_u32 s3, s3, 0
	s_waitcnt vmcnt(6)
	s_barrier
	ds_read_b128 v[32:35], v72 offset:32768
	ds_read_b128 v[40:43], v76 offset:32768
	ds_read_b128 v[36:39], v72 offset:36864
	ds_read_b128 v[44:47], v73 offset:32768
	ds_read_b128 v[52:55], v77 offset:32768
	ds_read_b128 v[48:51], v73 offset:36864
	s_waitcnt lgkmcnt(3)
	v_mfma_f32_32x32x16_bf16 v[0:15], v[32:35], v[40:43], v[0:15]
	ds_read_b128 v[56:59], v74 offset:32768
	ds_read_b128 v[64:67], v78 offset:32768
	v_mfma_f32_32x32x16_bf16 v[16:31], v[36:39], v[40:43], v[16:31]
	ds_read_b128 v[60:63], v74 offset:36864
	s_waitcnt lgkmcnt(3)
	v_mfma_f32_32x32x16_bf16 v[0:15], v[44:47], v[52:55], v[0:15]
	ds_read_b128 v[32:35], v75 offset:32768
	ds_read_b128 v[40:43], v79 offset:32768
	v_mfma_f32_32x32x16_bf16 v[16:31], v[48:51], v[52:55], v[16:31]
	ds_read_b128 v[36:39], v75 offset:36864
	s_waitcnt lgkmcnt(3)
	v_mfma_f32_32x32x16_bf16 v[0:15], v[56:59], v[64:67], v[0:15]
	v_mfma_f32_32x32x16_bf16 v[16:31], v[60:63], v[64:67], v[16:31]
	s_waitcnt lgkmcnt(0)
	v_mfma_f32_32x32x16_bf16 v[0:15], v[32:35], v[40:43], v[0:15]
	v_mfma_f32_32x32x16_bf16 v[16:31], v[36:39], v[40:43], v[16:31]
	s_barrier
	s_add_u32 m0, s6, 0x8000
	s_nop 0
	global_load_lds_dwordx4 v68, s[0:1] offset:0
	global_load_lds_dwordx4 v69, s[0:1] offset:1024
	global_load_lds_dwordx4 v70, s[0:1] offset:2048
	global_load_lds_dwordx4 v71, s[0:1] offset:3072
	s_add_u32 m0, s7, 0x8000
	s_nop 0
	global_load_lds_dwordx4 v68, s[2:3] offset:0
	global_load_lds_dwordx4 v69, s[2:3] offset:1024
	s_add_u32 s0, s0, 0x80
	s_addc_u32 s1, s1, 0
	s_add_u32 s2, s2, 0x80
	s_addc_u32 s3, s3, 0
	s_sub_u32 s8, s8, 1
	s_cmp_lg_u32 s8, 0
	s_cbranch_scc1 .Lgeo_loop
	s_waitcnt vmcnt(6)
	s_barrier
	ds_read_b128 v[32:35], v72 offset:0
	ds_read_b128 v[40:43], v76 offset:0
	ds_read_b128 v[36:39], v72 offset:4096
	ds_read_b128 v[44:47], v73 offset:0
	ds_read_b128 v[52:55], v77 offset:0
	ds_read_b128 v[48:51], v73 offset:4096
	s_waitcnt lgkmcnt(3)
	v_mfma_f32_32x32x16_bf16 v[0:15], v[32:35], v[40:43], v[0:15]
	ds_read_b128 v[56:59], v74 offset:0
	ds_read_b128 v[64:67], v78 offset:0
	v_mfma_f32_32x32x16_bf16 v[16:31], v[36:39], v[40:43], v[16:31]
	ds_read_b128 v[60:63], v74 offset:4096
	s_waitcnt lgkmcnt(3)
	v_mfma_f32_32x32x16_bf16 v[0:15], v[44:47], v[52:55], v[0:15]
	ds_read_b128 v[32:35], v75 offset:0
	ds_read_b128 v[40:43], v79 offset:0
	v_mfma_f32_32x32x16_bf16 v[16:31], v[48:51], v[52:55], v[16:31]
	ds_read_b128 v[36:39], v75 offset:4096
	s_waitcnt lgkmcnt(3)
	v_mfma_f32_32x32x16_bf16 v[0:15], v[56:59], v[64:67], v[0:15]
	v_mfma_f32_32x32x16_bf16 v[16:31], v[60:63], v[64:67], v[16:31]
	s_waitcnt lgkmcnt(0)
	v_mfma_f32_32x32x16_bf16 v[0:15], v[32:35], v[40:43], v[0:15]
	v_mfma_f32_32x32x16_bf16 v[16:31], v[36:39], v[40:43], v[16:31]
	s_barrier
	s_waitcnt vmcnt(0)
	s_barrier
	ds_read_b128 v[32:35], v72 offset:32768
	ds_read_b128 v[40:43], v76 offset:32768
	ds_read_b128 v[36:39], v72 offset:36864
	ds_read_b128 v[44:47], v73 offset:32768
	ds_read_b128 v[52:55], v77 offset:32768
	ds_read_b128 v[48:51], v73 offset:36864
	s_waitcnt lgkmcnt(3)
	v_mfma_f32_32x32x16_bf16 v[0:15], v[32:35], v[40:43], v[0:15]
	ds_read_b128 v[56:59], v74 offset:32768
	ds_read_b128 v[64:67], v78 offset:32768
	v_mfma_f32_32x32x16_bf16 v[16:31], v[36:39], v[40:43], v[16:31]
	ds_read_b128 v[60:63], v74 offset:36864
	s_waitcnt lgkmcnt(3)
	v_mfma_f32_32x32x16_bf16 v[0:15], v[44:47], v[52:55], v[0:15]
	ds_read_b128 v[32:35], v75 offset:32768
	ds_read_b128 v[40:43], v79 offset:32768
	v_mfma_f32_32x32x16_bf16 v[16:31], v[48:51], v[52:55], v[16:31]
	ds_read_b128 v[36:39], v75 offset:36864
	s_waitcnt lgkmcnt(3)
	v_mfma_f32_32x32x16_bf16 v[0:15], v[56:59], v[64:67], v[0:15]
	v_mfma_f32_32x32x16_bf16 v[16:31], v[60:63], v[64:67], v[16:31]
	s_waitcnt lgkmcnt(0)
	v_mfma_f32_32x32x16_bf16 v[0:15], v[32:35], v[40:43], v[0:15]
	v_mfma_f32_32x32x16_bf16 v[16:31], v[36:39], v[40:43], v[16:31]
	s_barrier
	s_nop 7
	s_nop 7
	s_branch .Leo_epi
.Leo_epi:
	v_lshl_or_b32 v80, v183, 3, v191
	v_and_b32_e32 v81, 31, v80
	v_bfe_u32 v82, v80, 6, 1
	v_mul_u32_u24_e32 v82, 32, v82
	v_add_u32_e32 v82, v82, v81
	v_lshlrev_b32_e32 v84, 2, v82
	v_bfe_u32 v82, v80, 7, 1
	v_lshlrev_b32_e32 v82, 4, v82
	v_bfe_u32 v87, v80, 5, 1
	v_or_b32_e32 v82, v82, v87
	v_lshl_add_u32 v83, v82, 14, v84
	s_sub_u32 s100, s10, 0x2000
	s_lshr_b32 s100, s100, 11
	s_add_u32 s100, s100, 1
	s_cmp_lt_u32 s10, 0x2000
	s_cmov_b32 s100, 0
	s_mul_i32 s100, s100, 0x6000
	s_lshl_b32 s101, s11, 2
	s_add_u32 s100, s100, s101
	s_add_u32 s100, s100, 0x3442000
	v_add_u32_e32 v84, s100, v84
	global_load_dword v85, v84, s[90:91]
	s_lshl_b32 s100, s10, 12
	s_add_u32 s100, s100, s101
	s_add_u32 s98, s88, s100
	s_addc_u32 s99, s89, 0
	s_lshl_b32 s100, s10, 12
	s_add_u32 s100, s100, s101
	s_sub_u32 s15, s100, 0x2000000
	s_cmp_lt_u32 s10, 0x2000
	s_cselect_b32 s15, s100, s15
	s_cselect_b32 s100, s72, s74
	s_cselect_b32 s101, s73, s75
	s_add_u32 s100, s100, s15
	s_addc_u32 s101, s101, 0
	s_mov_b32 s16, s100
	s_mov_b32 s17, s101
	global_load_dword v96, v83, s[16:17] offset:0
	s_add_u32 s16, s16, 0x1000
	s_addc_u32 s17, s17, 0
	global_load_dword v97, v83, s[16:17] offset:0
	s_add_u32 s16, s16, 0x1000
	s_addc_u32 s17, s17, 0
	global_load_dword v98, v83, s[16:17] offset:0
	s_add_u32 s16, s16, 0x1000
	s_addc_u32 s17, s17, 0
	global_load_dword v99, v83, s[16:17] offset:0
	s_add_u32 s16, s16, 0x5000
	s_addc_u32 s17, s17, 0
	global_load_dword v100, v83, s[16:17] offset:0
	s_add_u32 s16, s16, 0x1000
	s_addc_u32 s17, s17, 0
	global_load_dword v101, v83, s[16:17] offset:0
	s_add_u32 s16, s16, 0x1000
	s_addc_u32 s17, s17, 0
	global_load_dword v102, v83, s[16:17] offset:0
	s_add_u32 s16, s16, 0x1000
	s_addc_u32 s17, s17, 0
	global_load_dword v103, v83, s[16:17] offset:0
	s_add_u32 s16, s16, 0x5000
	s_addc_u32 s17, s17, 0
	global_load_dword v104, v83, s[16:17] offset:0
	s_add_u32 s16, s16, 0x1000
	s_addc_u32 s17, s17, 0
	global_load_dword v105, v83, s[16:17] offset:0
	s_add_u32 s16, s16, 0x1000
	s_addc_u32 s17, s17, 0
	global_load_dword v106, v83, s[16:17] offset:0
	s_add_u32 s16, s16, 0x1000
	s_addc_u32 s17, s17, 0
	global_load_dword v107, v83, s[16:17] offset:0
	s_add_u32 s16, s16, 0x5000
	s_addc_u32 s17, s17, 0
	global_load_dword v108, v83, s[16:17] offset:0
	s_add_u32 s16, s16, 0x1000
	s_addc_u32 s17, s17, 0
	global_load_dword v109, v83, s[16:17] offset:0
	s_add_u32 s16, s16, 0x1000
	s_addc_u32 s17, s17, 0
	global_load_dword v110, v83, s[16:17] offset:0
	s_add_u32 s16, s16, 0x1000
	s_addc_u32 s17, s17, 0
	global_load_dword v111, v83, s[16:17] offset:0
	s_add_u32 s16, s16, 0x5000
	s_addc_u32 s17, s17, 0
	global_load_dword v112, v83, s[16:17] offset:0
	s_add_u32 s16, s16, 0x1000
	s_addc_u32 s17, s17, 0
	global_load_dword v113, v83, s[16:17] offset:0
	s_add_u32 s16, s16, 0x1000
	s_addc_u32 s17, s17, 0
	global_load_dword v114, v83, s[16:17] offset:0
	s_add_u32 s16, s16, 0x1000
	s_addc_u32 s17, s17, 0
	global_load_dword v115, v83, s[16:17] offset:0
	s_add_u32 s16, s16, 0x5000
	s_addc_u32 s17, s17, 0
	global_load_dword v116, v83, s[16:17] offset:0
	s_add_u32 s16, s16, 0x1000
	s_addc_u32 s17, s17, 0
	global_load_dword v117, v83, s[16:17] offset:0
	s_add_u32 s16, s16, 0x1000
	s_addc_u32 s17, s17, 0
	global_load_dword v118, v83, s[16:17] offset:0
	s_add_u32 s16, s16, 0x1000
	s_addc_u32 s17, s17, 0
	global_load_dword v119, v83, s[16:17] offset:0
	s_add_u32 s16, s16, 0x5000
	s_addc_u32 s17, s17, 0
	global_load_dword v120, v83, s[16:17] offset:0
	s_add_u32 s16, s16, 0x1000
	s_addc_u32 s17, s17, 0
	global_load_dword v121, v83, s[16:17] offset:0
	s_add_u32 s16, s16, 0x1000
	s_addc_u32 s17, s17, 0
	global_load_dword v122, v83, s[16:17] offset:0
	s_add_u32 s16, s16, 0x1000
	s_addc_u32 s17, s17, 0
	global_load_dword v123, v83, s[16:17] offset:0
	s_add_u32 s16, s16, 0x5000
	s_addc_u32 s17, s17, 0
	global_load_dword v124, v83, s[16:17] offset:0
	s_add_u32 s16, s16, 0x1000
	s_addc_u32 s17, s17, 0
	global_load_dword v125, v83, s[16:17] offset:0
	s_add_u32 s16, s16, 0x1000
	s_addc_u32 s17, s17, 0
	global_load_dword v126, v83, s[16:17] offset:0
	s_add_u32 s16, s16, 0x1000
	s_addc_u32 s17, s17, 0
	global_load_dword v127, v83, s[16:17] offset:0
	s_waitcnt vmcnt(0)
	v_fmac_f32_e32 v96, v85, v0
	v_fmac_f32_e32 v97, v85, v1
	v_fmac_f32_e32 v98, v85, v2
	v_fmac_f32_e32 v99, v85, v3
	v_fmac_f32_e32 v100, v85, v4
	v_fmac_f32_e32 v101, v85, v5
	v_fmac_f32_e32 v102, v85, v6
	v_fmac_f32_e32 v103, v85, v7
	v_fmac_f32_e32 v104, v85, v8
	v_fmac_f32_e32 v105, v85, v9
	v_fmac_f32_e32 v106, v85, v10
	v_fmac_f32_e32 v107, v85, v11
	v_fmac_f32_e32 v108, v85, v12
	v_fmac_f32_e32 v109, v85, v13
	v_fmac_f32_e32 v110, v85, v14
	v_fmac_f32_e32 v111, v85, v15
	v_fmac_f32_e32 v112, v85, v16
	v_fmac_f32_e32 v113, v85, v17
	v_fmac_f32_e32 v114, v85, v18
	v_fmac_f32_e32 v115, v85, v19
	v_fmac_f32_e32 v116, v85, v20
	v_fmac_f32_e32 v117, v85, v21
	v_fmac_f32_e32 v118, v85, v22
	v_fmac_f32_e32 v119, v85, v23
	v_fmac_f32_e32 v120, v85, v24
	v_fmac_f32_e32 v121, v85, v25
	v_fmac_f32_e32 v122, v85, v26
	v_fmac_f32_e32 v123, v85, v27
	v_fmac_f32_e32 v124, v85, v28
	v_fmac_f32_e32 v125, v85, v29
	v_fmac_f32_e32 v126, v85, v30
	v_fmac_f32_e32 v127, v85, v31
	s_mov_b32 s16, s98
	s_mov_b32 s17, s99
	global_store_dword v83, v96, s[16:17] offset:0
	s_add_u32 s16, s16, 0x1000
	s_addc_u32 s17, s17, 0
	global_store_dword v83, v97, s[16:17] offset:0
	s_add_u32 s16, s16, 0x1000
	s_addc_u32 s17, s17, 0
	global_store_dword v83, v98, s[16:17] offset:0
	s_add_u32 s16, s16, 0x1000
	s_addc_u32 s17, s17, 0
	global_store_dword v83, v99, s[16:17] offset:0
	s_add_u32 s16, s16, 0x5000
	s_addc_u32 s17, s17, 0
	global_store_dword v83, v100, s[16:17] offset:0
	s_add_u32 s16, s16, 0x1000
	s_addc_u32 s17, s17, 0
	global_store_dword v83, v101, s[16:17] offset:0
	s_add_u32 s16, s16, 0x1000
	s_addc_u32 s17, s17, 0
	global_store_dword v83, v102, s[16:17] offset:0
	s_add_u32 s16, s16, 0x1000
	s_addc_u32 s17, s17, 0
	global_store_dword v83, v103, s[16:17] offset:0
	s_add_u32 s16, s16, 0x5000
	s_addc_u32 s17, s17, 0
	global_store_dword v83, v104, s[16:17] offset:0
	s_add_u32 s16, s16, 0x1000
	s_addc_u32 s17, s17, 0
	global_store_dword v83, v105, s[16:17] offset:0
	s_add_u32 s16, s16, 0x1000
	s_addc_u32 s17, s17, 0
	global_store_dword v83, v106, s[16:17] offset:0
	s_add_u32 s16, s16, 0x1000
	s_addc_u32 s17, s17, 0
	global_store_dword v83, v107, s[16:17] offset:0
	s_add_u32 s16, s16, 0x5000
	s_addc_u32 s17, s17, 0
	global_store_dword v83, v108, s[16:17] offset:0
	s_add_u32 s16, s16, 0x1000
	s_addc_u32 s17, s17, 0
	global_store_dword v83, v109, s[16:17] offset:0
	s_add_u32 s16, s16, 0x1000
	s_addc_u32 s17, s17, 0
	global_store_dword v83, v110, s[16:17] offset:0
	s_add_u32 s16, s16, 0x1000
	s_addc_u32 s17, s17, 0
	global_store_dword v83, v111, s[16:17] offset:0
	s_add_u32 s16, s16, 0x5000
	s_addc_u32 s17, s17, 0
	global_store_dword v83, v112, s[16:17] offset:0
	s_add_u32 s16, s16, 0x1000
	s_addc_u32 s17, s17, 0
	global_store_dword v83, v113, s[16:17] offset:0
	s_add_u32 s16, s16, 0x1000
	s_addc_u32 s17, s17, 0
	global_store_dword v83, v114, s[16:17] offset:0
	s_add_u32 s16, s16, 0x1000
	s_addc_u32 s17, s17, 0
	global_store_dword v83, v115, s[16:17] offset:0
	s_add_u32 s16, s16, 0x5000
	s_addc_u32 s17, s17, 0
	global_store_dword v83, v116, s[16:17] offset:0
	s_add_u32 s16, s16, 0x1000
	s_addc_u32 s17, s17, 0
	global_store_dword v83, v117, s[16:17] offset:0
	s_add_u32 s16, s16, 0x1000
	s_addc_u32 s17, s17, 0
	global_store_dword v83, v118, s[16:17] offset:0
	s_add_u32 s16, s16, 0x1000
	s_addc_u32 s17, s17, 0
	global_store_dword v83, v119, s[16:17] offset:0
	s_add_u32 s16, s16, 0x5000
	s_addc_u32 s17, s17, 0
	global_store_dword v83, v120, s[16:17] offset:0
	s_add_u32 s16, s16, 0x1000
	s_addc_u32 s17, s17, 0
	global_store_dword v83, v121, s[16:17] offset:0
	s_add_u32 s16, s16, 0x1000
	s_addc_u32 s17, s17, 0
	global_store_dword v83, v122, s[16:17] offset:0
	s_add_u32 s16, s16, 0x1000
	s_addc_u32 s17, s17, 0
	global_store_dword v83, v123, s[16:17] offset:0
	s_add_u32 s16, s16, 0x5000
	s_addc_u32 s17, s17, 0
	global_store_dword v83, v124, s[16:17] offset:0
	s_add_u32 s16, s16, 0x1000
	s_addc_u32 s17, s17, 0
	global_store_dword v83, v125, s[16:17] offset:0
	s_add_u32 s16, s16, 0x1000
	s_addc_u32 s17, s17, 0
	global_store_dword v83, v126, s[16:17] offset:0
	s_add_u32 s16, s16, 0x1000
	s_addc_u32 s17, s17, 0
	global_store_dword v83, v127, s[16:17] offset:0
	s_branch .Leo_next
.Leo_next:
	s_add_i32 s9, s9, s92
	s_cmpk_lt_i32 s9, 0x600
	s_cbranch_scc1 .Leo_item
